# v067 + the leading half raises its priority (s_setprio 1) behind its alignment barrier: its epilogue and unit set-up, the critical path between units, win the shared VALU over the trailing half's epil
# speedup vs baseline: 1.0019x; 1.0019x over previous
; #define PG8_BAR __builtin_amdgcn_s_barrier()
;     __device__ __forceinline__ void operator()(const f32x4 (&acc)[2][2][4][2], const Unit& u, int wr, int wc, int fr_in, int fq_in) const {
;         int fr = fr_in, fq = fq_in; asm volatile("" : "+v"(fr), "+v"(fq));
;         const int row0 = u.pm * BM + wr * 64 + fr;
;         if (u.pn >= 4 && u.pn <= 8) {
; template <class Epi, class Sched, bool ALIGN_EPI = false, bool SP2 = false>
; __device__ __forceinline__ void gemm_phase(PG8_LAS unsigned char* lds, const Gemm g, const Sched& S, const Epi& E) {
;     ...
;             }
;         }
;         if constexpr (ALIGN_EPI) { if (wr == 0) PG8_BAR; }
.Lpx_270:
	s_lshl_b32 s0, s78, 8
	v_mov_b32_e32 v223, v99
	v_mov_b32_e32 v224, v1
	s_add_i32 s0, s0, s6
	v_readlane_b32 s60, v251, 14
	v_add_u32_e32 v192, s0, v224
	s_add_i32 s0, s95, -4
	s_and_b64 vcc, exec, s[10:11]
	s_cbranch_vccz .LBB0_273
	s_barrier
	s_setprio 1

; #define GAS __attribute__((address_space(1)))
; __device__ __forceinline__ void unpack8(u32x4 w, f32x4& v0, f32x4& v1) { v0 = (f32x4){bflo(w.x), bfhi(w.x), bflo(w.y), bfhi(w.y)}; v1 = (f32x4){bflo(w.z), bfhi(w.z), bflo(w.w), bfhi(w.w)}; }
; #define PG8_BAR __builtin_amdgcn_s_barrier()
; #define GAS __attribute__((address_space(1)))
;     __device__ __forceinline__ void operator()(const f32x4 (&acc)[2][2][4][2], const Unit& u, int wr, int wc, int fr, int fq) const {
;         const int row0 = u.pm * BM + wr * 64 + fr, col0 = u.pn * BM + wc * 32 + 8 * fq;
;         f32x4 bv[2][2];
; #pragma unroll
;         for (int bj = 0; bj < 2; ++bj)
; #pragma unroll
;             for (int n = 0; n < 2; ++n) bv[bj][n] = *(const f32x4*)(bglu + col0 + bj * HALF + 4 * n);
;         const bf16_t* const zb = Z + (size_t)row0 * 1024 + col0; bf16_t* const sob = SO + (size_t)row0 * 1024 + col0;
; #pragma unroll
;         for (int ai = 0; ai < 2; ++ai)
; #pragma unroll
;             for (int m = 0; m < 4; ++m) { const size_t off = (size_t)(ai * HALF + m * 16) * 1024;
; #pragma unroll
;                 for (int bj = 0; bj < 2; ++bj) { f32x4 z0, z1; unpack8(*(const GAS u32x4*)(zb + off + bj * HALF), z0, z1);
; template <class Epi, class Sched, bool ALIGN_EPI = false, bool SP2 = false>
; __device__ __forceinline__ void gemm_phase(PG8_LAS unsigned char* lds, const Gemm g, const Sched& S, const Epi& E) {
;     ...
;         if constexpr (ALIGN_EPI) { if (wr == 0) PG8_BAR; }
.Lpx_936:
	v_lshl_or_b32 v160, s24, 8, v164
	v_ashrrev_i32_e32 v161, 31, v160
	v_lshl_add_u64 v[22:23], v[160:161], 2, s[8:9]
	global_load_dwordx4 v[34:37], v[22:23], off offset:16
	global_load_dwordx4 v[38:41], v[22:23], off
	global_load_dwordx4 v[14:17], v[22:23], off offset:528
	s_nop 0
	global_load_dwordx4 v[22:25], v[22:23], off offset:512
	v_lshl_add_u32 v162, s42, 8, v1
	v_ashrrev_i32_e32 v163, 31, v162
	v_lshlrev_b64 v[166:167], 11, v[162:163]
	v_lshl_add_u64 v[162:163], s[4:5], 0, v[166:167]
	v_lshlrev_b64 v[160:161], 1, v[160:161]
	v_lshl_add_u64 v[162:163], v[162:163], 0, v[160:161]
	global_load_dwordx4 v[184:187], v[162:163], off
	global_load_dwordx4 v[188:191], v[162:163], off offset:256
	v_add_co_u32_e32 v242, vcc, s94, v162
	v_addc_co_u32_e32 v243, vcc, 0, v163, vcc
	global_load_dwordx4 v[192:195], v[242:243], off
	global_load_dwordx4 v[196:199], v[242:243], off offset:256
	v_add_co_u32_e32 v242, vcc, s73, v162
	v_addc_co_u32_e32 v243, vcc, 0, v163, vcc
	global_load_dwordx4 v[200:203], v[242:243], off
	global_load_dwordx4 v[222:225], v[242:243], off offset:256
	v_add_co_u32_e32 v242, vcc, s93, v162
	v_addc_co_u32_e32 v243, vcc, 0, v163, vcc
	global_load_dwordx4 v[226:229], v[242:243], off
	global_load_dwordx4 v[230:233], v[242:243], off offset:256
	v_add_co_u32_e32 v242, vcc, s49, v162
	v_addc_co_u32_e32 v243, vcc, 0, v163, vcc
	global_load_dwordx4 v[234:237], v[242:243], off
	global_load_dwordx4 v[238:241], v[242:243], off offset:256
	v_lshl_add_u64 v[166:167], s[10:11], 0, v[166:167]
	v_lshl_add_u64 v[160:161], v[166:167], 0, v[160:161]
	v_readlane_b32 s90, v254, 50
	s_mov_b64 s[42:43], -1
	v_readlane_b32 s91, v254, 51
	s_and_b64 vcc, exec, s[12:13]
	s_cbranch_vccz .LBB0_939
	s_barrier
	s_setprio 1

; #define GAS __attribute__((address_space(1)))
; __device__ __forceinline__ void unpack8(u32x4 w, f32x4& v0, f32x4& v1) { v0 = (f32x4){bflo(w.x), bfhi(w.x), bflo(w.y), bfhi(w.y)}; v1 = (f32x4){bflo(w.z), bfhi(w.z), bflo(w.w), bfhi(w.w)}; }
; #define PG8_BAR __builtin_amdgcn_s_barrier()
; #define GAS __attribute__((address_space(1)))
;     __device__ __forceinline__ void operator()(const f32x4 (&acc)[2][2][4][2], const Unit& u, int wr, int wc, int fr, int fq) const {
;         const int row0 = u.pm * BM + wr * 64 + fr, col0 = u.pn * BM + wc * 32 + 8 * fq;
;         const bool samp = u.pm >= 32;
;         GAS unsigned* flag = (GAS unsigned*)(flags + 64 * (u.pn * 4 + (u.pm & 3)));
;         if (MODE == 1 && samp) {
;             unsigned spins = 0u;
;             while (__hip_atomic_load(flag, __ATOMIC_RELAXED, __HIP_MEMORY_SCOPE_AGENT) < 8u) { __builtin_amdgcn_s_sleep(2); if (++spins > (1u << 18)) break; }
;             __builtin_amdgcn_fence(__ATOMIC_ACQUIRE, "agent"); asm volatile("s_waitcnt vmcnt(0)" ::: "memory");
;         }
; #pragma unroll
;         for (int ai = 0; ai < 2; ++ai)
; #pragma unroll
;             for (int m = 0; m < 4; ++m) { const size_t r = (size_t)(row0 + ai * HALF + m * 16); const size_t off = r * 2048 + col0; const bf16_t* gp = P + r * NPJ + 2560 + MODE * 2048 + col0;
; #pragma unroll
;                 for (int bj = 0; bj < 2; ++bj) { f32x4 g0, g1; unpack8(*(const GAS u32x4*)(gp + bj * HALF), g0, g1);
; template <class Epi, class Sched, bool ALIGN_EPI = false, bool SP2 = false>
; __device__ __forceinline__ void gemm_phase(PG8_LAS unsigned char* lds, const Gemm g, const Sched& S, const Epi& E) {
;     ...
;         if constexpr (ALIGN_EPI) { if (wr == 0) PG8_BAR; }
.Lpx_1067:
	s_lshl_b32 s15, s91, 8
	v_or_b32_e32 v144, s15, v150
	v_lshl_add_u32 v146, s90, 8, v1
	v_ashrrev_i32_e32 v145, 31, v144
	v_mov_b64_e32 v[148:149], s[8:9]
	s_movk_i32 s95, 0x3400
	v_mad_i64_i32 v[148:149], s[0:1], v146, s95, v[148:149]
	v_lshlrev_b64 v[144:145], 1, v[144:145]
	v_lshl_add_u64 v[148:149], v[148:149], 0, v[144:145]
	s_movk_i32 s0, 0x1000
	v_add_co_u32_e32 v152, vcc, s0, v148
	s_cmp_gt_i32 s90, 31
	s_nop 0
	v_addc_co_u32_e32 v153, vcc, 0, v149, vcc
	global_load_dwordx4 v[222:225], v[152:153], off offset:1024
	global_load_dwordx4 v[226:229], v[152:153], off offset:1280
	v_add_co_u32_e32 v188, vcc, 0x34000, v152
	s_nop 1
	v_addc_co_u32_e32 v189, vcc, 0, v153, vcc
	global_load_dwordx4 v[230:233], v[188:189], off offset:1024
	global_load_dwordx4 v[234:237], v[188:189], off offset:1280
	v_add_co_u32_e32 v188, vcc, 0x68000, v152
	s_nop 1
	v_addc_co_u32_e32 v189, vcc, 0, v153, vcc
	global_load_dwordx4 v[238:241], v[188:189], off offset:1024
	global_load_dwordx4 v[242:245], v[188:189], off offset:1280
	v_add_co_u32_e32 v188, vcc, 0x9c000, v152
	s_nop 1
	v_addc_co_u32_e32 v189, vcc, 0, v153, vcc
	global_load_dwordx4 v[180:183], v[188:189], off offset:1024
	global_load_dwordx4 v[184:187], v[188:189], off offset:1280
	v_ashrrev_i32_e32 v147, 31, v146
	s_cselect_b64 s[52:53], -1, 0
	s_cmp_lt_i32 s90, 32
	s_cselect_b64 s[54:55], -1, 0
	s_mov_b64 s[42:43], -1
	s_and_b64 vcc, exec, s[12:13]
	s_cbranch_vccz .LBB0_1070
	s_barrier
	s_setprio 1

; #define GAS __attribute__((address_space(1)))
; #define PG8_BAR __builtin_amdgcn_s_barrier()
; #define GAS __attribute__((address_space(1)))
;     __device__ __forceinline__ void operator()(const f32x4 (&acc)[2][2][4][2], const Unit& u, int wr, int wc, int fr, int fq) const {
;         const int row0 = u.pm * BM + wr * 64 + fr, col0 = u.pn * BM + wc * 32 + 8 * fq;
;         const bool samp = u.pm >= 32;
;         GAS unsigned* flag = (GAS unsigned*)(flags + 64 * (u.pn * 4 + (u.pm & 3)));
; template <class Epi, class Sched, bool ALIGN_EPI = false, bool SP2 = false>
; __device__ __forceinline__ void gemm_phase(PG8_LAS unsigned char* lds, const Gemm g, const Sched& S, const Epi& E) {
;     ...
;         if constexpr (ALIGN_EPI) { if (wr == 0) PG8_BAR; }
.Lpx_1157:
	s_lshl_b32 s19, s91, 8
	v_readlane_b32 s60, v251, 14
	s_and_b64 vcc, exec, s[16:17]
	s_cbranch_vccz .LBB0_1160
	s_barrier
	s_setprio 1

; #define GAS __attribute__((address_space(1)))
; #define PG8_BAR __builtin_amdgcn_s_barrier()
; #define GAS __attribute__((address_space(1)))
;     __device__ __forceinline__ void operator()(const f32x4 (&acc)[2][2][4][2], const Unit& u, int wr, int wc, int fr, int fq) const {
;         const int col0 = u.pn * BM + wc * 32 + 8 * fq;
;         const bool part = u.slab >= 0;
; #pragma unroll
;         for (int ai = 0; ai < 2; ++ai) {
;             const int rb = u.pm * BM + ai * HALF + wr * 64;
;             const int cb = rb < 8192 ? (rb >> 11) : 4 + ((rb - 8192) >> 6);
;             const float* g = gmod + (size_t)cb * 12288 + col0;
;             f32x4 gv[2][2];
; #pragma unroll
;             for (int bj = 0; bj < 2; ++bj)
; #pragma unroll
;                 for (int n = 0; n < 2; ++n) gv[bj][n] = *(const GAS f32x4*)(g + bj * HALF + 4 * n);
; template <class Epi, class Sched, bool ALIGN_EPI = false, bool SP2 = false>
; __device__ __forceinline__ void gemm_phase(PG8_LAS unsigned char* lds, const Gemm g, const Sched& S, const Epi& E) {
;     ...
;         if constexpr (ALIGN_EPI) { if (wr == 0) PG8_BAR; }
.Lpx_1308:
	s_cmp_lt_i32 s78, 0
	s_cselect_b64 s[34:35], -1, 0
	s_lshl_b32 s11, s69, 8
	s_add_i32 s11, s11, s58
	s_add_i32 s13, s11, 0xffffe000
	s_lshr_b32 s1, s13, 6
	s_ashr_i32 s0, s11, 11
	s_add_i32 s1, s1, 4
	s_cmpk_lt_i32 s11, 0x2000
	s_cselect_b32 s0, s0, s1
	s_mul_hi_i32 s1, s0, 0xc000
	s_mul_i32 s0, s0, 0xc000
	v_lshl_or_b32 v164, s70, 8, v180
	s_add_u32 s0, s54, s0
	v_ashrrev_i32_e32 v165, 31, v164
	s_addc_u32 s1, s55, s1
	v_lshl_add_u64 v[136:137], v[164:165], 2, s[0:1]
	global_load_dwordx4 v[140:143], v[136:137], off offset:16
	global_load_dwordx4 v[144:147], v[136:137], off
	global_load_dwordx4 v[132:135], v[136:137], off offset:528
	s_nop 0
	global_load_dwordx4 v[136:139], v[136:137], off offset:512
	s_mov_b64 s[36:37], -1
	s_and_b64 vcc, exec, s[8:9]
	s_cbranch_vccz .LBB0_1311
	s_barrier
	s_setprio 1

; #define PG8_BAR __builtin_amdgcn_s_barrier()
;     __device__ __forceinline__ void operator()(const f32x4 (&acc)[2][2][4][2], const Unit& u, int wr, int wc, int fr, int fq) const {
;         const int row0 = u.pm * BM + wr * 64 + fr, col0 = u.pn * HALF + wc * 32 + 8 * fq;
;         bf16_t* const p0 = ACT + (size_t)row0 * 5632 + col0;
; template <class Epi, class Sched, bool ALIGN_EPI = false, bool SP2 = false>
; __device__ __forceinline__ void gemm_phase(PG8_LAS unsigned char* lds, const Gemm g, const Sched& S, const Epi& E) {
;     ...
;         if constexpr (ALIGN_EPI) { if (wr == 0) PG8_BAR; }
.Lpx_1458:
	v_lshl_add_u32 v145, s70, 8, v1
	v_lshl_or_b32 v144, s69, 7, v148
	v_mov_b64_e32 v[146:147], s[8:9]
	s_movk_i32 s0, 0x2c00
	v_mad_i64_i32 v[146:147], s[0:1], v145, s0, v[146:147]
	v_ashrrev_i32_e32 v145, 31, v144
	v_lshl_add_u64 v[144:145], v[144:145], 1, v[146:147]
	s_and_b64 vcc, exec, s[10:11]
	s_cbranch_vccz .LBB0_1461
	s_barrier
	s_setprio 1

; #define GAS __attribute__((address_space(1)))
; #define PG8_BAR __builtin_amdgcn_s_barrier()
; #define GAS __attribute__((address_space(1)))
;     __device__ __forceinline__ void operator()(const f32x4 (&acc)[2][2][4][2], const Unit& u, int wr, int wc, int fr, int fq) const {
;         const int col0 = u.pn * BM + wc * 32 + 8 * fq;
;         const bool part = u.slab >= 0;
; #pragma unroll
;         for (int ai = 0; ai < 2; ++ai) {
;             const int rb = u.pm * BM + ai * HALF + wr * 64;
;             const int cb = rb < 8192 ? (rb >> 11) : 4 + ((rb - 8192) >> 6);
;             const float* g = gmod + (size_t)cb * 12288 + col0;
;             f32x4 gv[2][2];
; #pragma unroll
;             for (int bj = 0; bj < 2; ++bj)
; #pragma unroll
;                 for (int n = 0; n < 2; ++n) gv[bj][n] = *(const GAS f32x4*)(g + bj * HALF + 4 * n);
; template <class Epi, class Sched, bool ALIGN_EPI = false, bool SP2 = false>
; __device__ __forceinline__ void gemm_phase(PG8_LAS unsigned char* lds, const Gemm g, const Sched& S, const Epi& E) {
;     ...
;         if constexpr (ALIGN_EPI) { if (wr == 0) PG8_BAR; }
.Lpx_1654:
	s_cmp_lt_i32 s78, 0
	s_cselect_b64 s[34:35], -1, 0
	s_lshl_b32 s15, s71, 8
	s_add_i32 s15, s15, s59
	s_add_i32 s42, s15, 0xffffe000
	s_lshr_b32 s1, s42, 6
	s_ashr_i32 s0, s15, 11
	s_add_i32 s1, s1, 4
	s_cmpk_lt_i32 s15, 0x2000
	s_cselect_b32 s0, s0, s1
	s_mul_hi_i32 s1, s0, 0xc000
	s_mul_i32 s0, s0, 0xc000
	v_lshl_or_b32 v180, s75, 8, v188
	s_add_u32 s0, s55, s0
	v_ashrrev_i32_e32 v181, 31, v180
	s_addc_u32 s1, s56, s1
	v_lshl_add_u64 v[136:137], v[180:181], 2, s[0:1]
	global_load_dwordx4 v[140:143], v[136:137], off offset:16
	global_load_dwordx4 v[144:147], v[136:137], off
	global_load_dwordx4 v[132:135], v[136:137], off offset:528
	s_nop 0
	global_load_dwordx4 v[136:139], v[136:137], off offset:512
	s_and_b64 vcc, exec, s[12:13]
	s_cbranch_vccz .LBB0_1657
	s_barrier
	s_setprio 1
